# g2 first-chunk staging loads batched + g2 epilogue partial sums preloaded
# speedup vs baseline: 1.1223x; 1.0034x over previous
; #define LAS __attribute__((address_space(3)))
; __device__ __forceinline__ void g2_stage(LAS unsigned char* buf, const unsigned char* ub, const bf16* zsrc  , int ht, int nthr) {
;     for (int c = ht; c < 2048; c += nthr) { const int mat = c >> 9, w = c & 511, row = w >> 3, seg = w & 7;
;         *(LAS u32x4*)(buf + mat * G2_MAT + row * 144 + seg * 16) = *(const u32x4*)(ub + mat * 8192 + row * 128 + seg * 16); }
;     for (int c = ht; c < 1024; c += nthr) { const int row = c >> 4, seg = c & 15;
;         *(LAS u32x4*)(buf + G2_UV + row * 272 + seg * 16) = *(const u32x4*)(ub + 32768 + row * 256 + seg * 16); }
;     for (int c = ht; c < 512; c += nthr) { const int row = c >> 3, seg = c & 7;
;         *(LAS u32x4*)(buf + G2_Z + row * 144 + seg * 16) = *(const u32x4*)((const unsigned char*)(zsrc + (size_t)row * HLD) + seg * 16); }
;     if (ht == 0) *(LAS float*)(buf + G2_GAM) = *(const float*)(ub + 49152);
; }
; __device__ __forceinline__ void g2_phase(const PP P, int l, LAS unsigned char* lds) {
;     ...
;         g2_stage(lds, gs0, z0, tid, 512);
.LBB0_105:
	s_or_b64 exec, exec, s[26:27]
	s_load_dwordx2 s[22:23], s[0:1], 0x80
	s_waitcnt lgkmcnt(0)
	s_add_i32 s24, s66, 0x7c0
	v_lshl_add_u64 v[26:27], v[108:109], 2, s[22:23]
	global_load_dword v149, v[26:27], off
	s_lshl_b32 s25, s66, 5
	s_and_b64 s[22:23], s[2:3], exec
	s_cselect_b32 s22, s24, s25
	s_mul_i32 s58, s22, 0xc100
	s_mul_hi_i32 s59, s22, 0xc100
	s_add_u32 s22, s60, s58
	s_addc_u32 s23, s61, s59
	v_add_u32_e32 v42, 0, v177
	v_ashrrev_i32_e32 v40, 9, v42
	v_lshlrev_b32_e32 v32, 13, v40
	v_bfe_u32 v41, v42, 3, 6
	v_ashrrev_i32_e32 v33, 31, v32
	v_lshlrev_b32_e32 v24, 7, v41
	v_lshl_add_u64 v[32:33], s[22:23], 0, v[32:33]
	v_lshl_add_u64 v[32:33], v[32:33], 0, v[24:25]
	v_and_b32_e32 v24, 0x70, v139
	v_lshl_add_u64 v[32:33], v[32:33], 0, v[24:25]
	global_load_dwordx4 v[200:203], v[32:33], off
	v_mad_i32_i24 v40, v40, s89, 0
	v_mul_u32_u24_e32 v41, 0x90, v41
	v_add3_u32 v232, v40, v41, v24
	v_add_u32_e32 v42, 512, v177
	v_ashrrev_i32_e32 v40, 9, v42
	v_lshlrev_b32_e32 v32, 13, v40
	v_bfe_u32 v41, v42, 3, 6
	v_ashrrev_i32_e32 v33, 31, v32
	v_lshlrev_b32_e32 v24, 7, v41
	v_lshl_add_u64 v[32:33], s[22:23], 0, v[32:33]
	v_lshl_add_u64 v[32:33], v[32:33], 0, v[24:25]
	v_and_b32_e32 v24, 0x70, v139
	v_lshl_add_u64 v[32:33], v[32:33], 0, v[24:25]
	global_load_dwordx4 v[204:207], v[32:33], off
	v_mad_i32_i24 v40, v40, s89, 0
	v_mul_u32_u24_e32 v41, 0x90, v41
	v_add3_u32 v233, v40, v41, v24
	v_add_u32_e32 v42, 1024, v177
	v_ashrrev_i32_e32 v40, 9, v42
	v_lshlrev_b32_e32 v32, 13, v40
	v_bfe_u32 v41, v42, 3, 6
	v_ashrrev_i32_e32 v33, 31, v32
	v_lshlrev_b32_e32 v24, 7, v41
	v_lshl_add_u64 v[32:33], s[22:23], 0, v[32:33]
	v_lshl_add_u64 v[32:33], v[32:33], 0, v[24:25]
	v_and_b32_e32 v24, 0x70, v139
	v_lshl_add_u64 v[32:33], v[32:33], 0, v[24:25]
	global_load_dwordx4 v[208:211], v[32:33], off
	v_mad_i32_i24 v40, v40, s89, 0
	v_mul_u32_u24_e32 v41, 0x90, v41
	v_add3_u32 v234, v40, v41, v24
	v_add_u32_e32 v42, 1536, v177
	v_ashrrev_i32_e32 v40, 9, v42
	v_lshlrev_b32_e32 v32, 13, v40
	v_bfe_u32 v41, v42, 3, 6
	v_ashrrev_i32_e32 v33, 31, v32
	v_lshlrev_b32_e32 v24, 7, v41
	v_lshl_add_u64 v[32:33], s[22:23], 0, v[32:33]
	v_lshl_add_u64 v[32:33], v[32:33], 0, v[24:25]
	v_and_b32_e32 v24, 0x70, v139
	v_lshl_add_u64 v[32:33], v[32:33], 0, v[24:25]
	global_load_dwordx4 v[212:215], v[32:33], off
	v_mad_i32_i24 v40, v40, s89, 0
	v_mul_u32_u24_e32 v41, 0x90, v41
	v_add3_u32 v235, v40, v41, v24
	s_add_u32 s26, s22, 0x8000
	s_addc_u32 s27, s23, 0
	v_add_u32_e32 v42, 0, v177
	v_ashrrev_i32_e32 v40, 4, v42
	v_lshlrev_b32_e32 v32, 8, v40
	v_ashrrev_i32_e32 v33, 31, v32
	v_and_b32_e32 v24, 0xf0, v139
	v_lshl_add_u64 v[32:33], s[26:27], 0, v[32:33]
	v_lshl_add_u64 v[32:33], v[32:33], 0, v[24:25]
	global_load_dwordx4 v[216:219], v[32:33], off
	v_mul_lo_u32 v40, v40, s88
	v_add3_u32 v236, 0, v40, v24
	v_add_u32_e32 v42, 512, v177
	v_ashrrev_i32_e32 v40, 4, v42
	v_lshlrev_b32_e32 v32, 8, v40
	v_ashrrev_i32_e32 v33, 31, v32
	v_and_b32_e32 v24, 0xf0, v139
	v_lshl_add_u64 v[32:33], s[26:27], 0, v[32:33]
	v_lshl_add_u64 v[32:33], v[32:33], 0, v[24:25]
	global_load_dwordx4 v[220:223], v[32:33], off
	v_mul_lo_u32 v40, v40, s88
	v_add3_u32 v237, 0, v40, v24
	s_mul_i32 s24, s57, 0x1200
	s_mul_hi_u32 s25, s56, 0x1200
	s_add_i32 s69, s25, s24
	s_mul_i32 s70, s56, 0x1200
	s_add_u32 s24, s48, s70
	s_addc_u32 s25, s49, s69
	s_lshl_b32 s26, s30, 1
	s_add_u32 s24, s24, s26
	s_addc_u32 s25, s25, 0
	s_add_u32 s24, s24, 0x10109350
	s_addc_u32 s25, s25, 0
	v_ashrrev_i32_e32 v40, 3, v177
	v_mov_b64_e32 v[32:33], s[24:25]
	v_and_b32_e32 v24, 0x70, v139
	v_mad_i64_i32 v[32:33], s[30:31], v40, s99, v[32:33]
	v_lshl_add_u64 v[32:33], v[32:33], 0, v[24:25]
	global_load_dwordx4 v[224:227], v[32:33], off
	v_mul_lo_u32 v40, v40, s98
	v_add3_u32 v238, 0, v40, v24
	s_and_saveexec_b64 s[26:27], s[16:17]
	v_mov_b32_e32 v24, 0xc000
	global_load_dword v228, v24, s[22:23]
	s_or_b64 exec, exec, s[26:27]
	s_waitcnt vmcnt(0)
	ds_write_b128 v232, v[200:203]
	ds_write_b128 v233, v[204:207]
	ds_write_b128 v234, v[208:211]
	ds_write_b128 v235, v[212:215]
	ds_write_b128 v236, v[216:219] offset:36864
	ds_write_b128 v237, v[220:223] offset:36864
	ds_write_b128 v238, v[224:227] offset:54272
	s_and_saveexec_b64 s[26:27], s[16:17]
	ds_write_b32 v25, v228 offset:63488
	s_or_b64 exec, exec, s[26:27]
	v_mov_b32_e32 v26, v25
	v_mov_b32_e32 v27, v25
	v_mov_b32_e32 v24, v25
	v_mov_b64_e32 v[90:91], v[26:27]
	v_mov_b64_e32 v[86:87], v[26:27]
	v_mov_b64_e32 v[82:83], v[26:27]
	v_mov_b64_e32 v[78:79], v[26:27]
	v_mov_b64_e32 v[74:75], v[26:27]
	v_mov_b64_e32 v[70:71], v[26:27]
	v_mov_b64_e32 v[62:63], v[26:27]
	v_mov_b64_e32 v[58:59], v[26:27]
	v_mov_b64_e32 v[54:55], v[26:27]
	v_mov_b64_e32 v[50:51], v[26:27]
	v_mov_b64_e32 v[46:47], v[26:27]
	v_mov_b64_e32 v[42:43], v[26:27]
	v_mov_b64_e32 v[34:35], v[26:27]
	v_mov_b64_e32 v[66:67], v[26:27]
	s_nor_b64 s[28:29], s[6:7], s[2:3]
	v_mov_b32_e32 v147, 0
	v_mov_b64_e32 v[88:89], v[24:25]
	v_mov_b64_e32 v[84:85], v[24:25]
	v_mov_b64_e32 v[80:81], v[24:25]
	v_mov_b64_e32 v[76:77], v[24:25]
	v_mov_b64_e32 v[72:73], v[24:25]
	v_mov_b64_e32 v[68:69], v[24:25]
	v_mov_b64_e32 v[60:61], v[24:25]
	v_mov_b64_e32 v[56:57], v[24:25]
	v_mov_b64_e32 v[52:53], v[24:25]
	v_mov_b64_e32 v[48:49], v[24:25]
	v_mov_b64_e32 v[44:45], v[24:25]
	v_mov_b64_e32 v[40:41], v[24:25]
	v_mov_b64_e32 v[32:33], v[24:25]
	v_mov_b64_e32 v[64:65], v[24:25]
	s_and_saveexec_b64 s[26:27], s[28:29]
	s_cbranch_execz .LBB0_119
; __device__ __forceinline__ void g2_load(u32x4 (&r)[14], float& gam, const unsigned char* ub, const bf16* zsrc, int ht) {
;     const unsigned go = 16u * ht, gz = (ht >> 3) * (HLD * 2) + (ht & 7) * 16;
; #pragma unroll
;     for (int i = 0; i < 8; ++i) r[i] = *(const u32x4*)(ub + i * 4096 + go);
; #pragma unroll
;     for (int i = 0; i < 4; ++i) r[8 + i] = *(const u32x4*)(ub + 32768 + i * 4096 + go);
; #pragma unroll
;     for (int i = 0; i < 2; ++i) r[12 + i] = *(const u32x4*)((const unsigned char*)zsrc + (size_t)i * 32 * HLD * 2 + gz);
;     gam = *(const float*)(ub + 49152);
; }
; __device__ __forceinline__ void g2_phase(const PP P, int l, LAS unsigned char* lds) {
;     ...
;         if (!act && nch > 1) g2_load(hr_, hgam, gs0 + GUNIT, z0 + (size_t)64 * HLD, tid - 256);
	v_lshl_add_u64 v[26:27], s[22:23], 0, v[110:111]
	v_add_co_u32_e32 v32, vcc, 0xc000, v26
	s_mov_b32 s28, 0x10000
	s_nop 0
	v_addc_co_u32_e32 v33, vcc, 0, v27, vcc
	v_add_co_u32_e32 v34, vcc, 0xd000, v26
	v_mov_b32_e32 v24, 0x18000
	s_nop 0
	v_addc_co_u32_e32 v35, vcc, 0, v27, vcc
	v_add_co_u32_e32 v40, vcc, 0xe000, v26
	global_load_dwordx4 v[64:67], v[32:33], off offset:256
	s_nop 0
	global_load_dwordx4 v[32:35], v[34:35], off offset:256
	v_addc_co_u32_e32 v41, vcc, 0, v27, vcc
	v_add_co_u32_e32 v44, vcc, 0xf000, v26
	s_nop 1
	v_addc_co_u32_e32 v45, vcc, 0, v27, vcc
	v_add_co_u32_e32 v48, vcc, s28, v26
	global_load_dwordx4 v[40:43], v[40:41], off offset:256
	s_nop 0
	global_load_dwordx4 v[44:47], v[44:45], off offset:256
	v_addc_co_u32_e32 v49, vcc, 0, v27, vcc
	v_add_co_u32_e32 v52, vcc, 0x11000, v26
	s_nop 1
	v_addc_co_u32_e32 v53, vcc, 0, v27, vcc
	v_add_co_u32_e32 v56, vcc, 0x12000, v26
	global_load_dwordx4 v[48:51], v[48:49], off offset:256
	s_nop 0
	global_load_dwordx4 v[52:55], v[52:53], off offset:256
	v_addc_co_u32_e32 v57, vcc, 0, v27, vcc
	v_add_co_u32_e32 v60, vcc, 0x13000, v26
	s_nop 1
	v_addc_co_u32_e32 v61, vcc, 0, v27, vcc
	v_add_co_u32_e32 v68, vcc, 0x14000, v26
	global_load_dwordx4 v[56:59], v[56:57], off offset:256
	s_nop 0
	global_load_dwordx4 v[60:63], v[60:61], off offset:256
	v_addc_co_u32_e32 v69, vcc, 0, v27, vcc
	v_add_co_u32_e32 v72, vcc, 0x15000, v26
	s_nop 1
	v_addc_co_u32_e32 v73, vcc, 0, v27, vcc
	v_add_co_u32_e32 v76, vcc, 0x16000, v26
	global_load_dwordx4 v[68:71], v[68:69], off offset:256
	s_nop 0
	global_load_dwordx4 v[72:75], v[72:73], off offset:256
	v_addc_co_u32_e32 v77, vcc, 0, v27, vcc
	v_add_co_u32_e32 v26, vcc, 0x17000, v26
	s_nop 1
	v_addc_co_u32_e32 v27, vcc, 0, v27, vcc
	global_load_dwordx4 v[76:79], v[76:77], off offset:256
	s_nop 0
	global_load_dwordx4 v[80:83], v[26:27], off offset:256
	v_lshl_add_u64 v[26:27], s[24:25], 0, v[112:113]
	v_add_co_u32_e32 v84, vcc, 0x48000, v26
	s_nop 1
	v_addc_co_u32_e32 v85, vcc, 0, v27, vcc
	v_add_co_u32_e32 v26, vcc, 0x6c000, v26
	s_nop 1
	v_addc_co_u32_e32 v27, vcc, 0, v27, vcc
	global_load_dwordx4 v[84:87], v[84:85], off
	s_nop 0
	global_load_dwordx4 v[88:91], v[26:27], off
	global_load_dword v147, v24, s[22:23] offset:256

; #define LAS __attribute__((address_space(3)))
; __device__ __forceinline__ unsigned f2bf(float f) { const f32x2_ v = {f, 0.f}; const bf16x2_ b = __builtin_convertvector(v, bf16x2_); return __builtin_bit_cast(unsigned, b) & 0xffffu; }
; __device__ __forceinline__ float siluf_(float x) { return x * sigmoidf_(x); }
; __device__ __forceinline__ void g2_phase(const PP P, int l, LAS unsigned char* lds) {
;     ...
;             if (act) {
; #pragma unroll
;                 for (int mi = 0; mi < 4; ++mi)
; #pragma unroll
;                     for (int j = 0; j < 4; ++j) { const int i = 16 * mi + fq * 4 + j; LAS float* rp = red + (n & 1) * 256 + i;
;                         const float tot = rp[0] + rp[64] + rp[128] + rp[192]; const float rinv = __builtin_amdgcn_rsqf(tot * (1.0f / 64.0f) + 1e-6f);
;                         if (i < L) { const size_t row = seq0 + (size_t)n * 64 + i;
;                             MIX[row * 1024 + 512 + h * 64 + dv] = (bf16)f2bf(O[mi][j] * rinv * gnw * siluf_(zr[mi][j])); } }
;             }
.LBB0_162:
	s_or_b64 exec, exec, s[56:57]
	s_waitcnt lgkmcnt(0)
	s_barrier
	s_and_saveexec_b64 s[56:57], s[6:7]
	s_cbranch_execz .LBB0_120
	v_lshl_add_u32 v24, s71, 10, v125
	ds_read_b128 v[178:181], v24
	ds_read_b128 v[182:185], v24 offset:256
	ds_read_b128 v[186:189], v24 offset:512
	ds_read_b128 v[190:193], v24 offset:768
	v_mul_f32_e32 v158, 0xbfb8aa3b, v93
	v_exp_f32_e32 v158, v158
	s_waitcnt lgkmcnt(2)
	v_add_f32_e32 v148, v178, v182
	s_waitcnt lgkmcnt(1)
	v_add_f32_e32 v148, v148, v186
	s_waitcnt lgkmcnt(0)
	ds_read_b128 v[196:199], v24 offset:64
	ds_read_b128 v[200:203], v24 offset:320
	ds_read_b128 v[204:207], v24 offset:576
	ds_read_b128 v[208:211], v24 offset:832
	ds_read_b128 v[212:215], v24 offset:128
	ds_read_b128 v[216:219], v24 offset:384
	ds_read_b128 v[220:223], v24 offset:640
	ds_read_b128 v[224:227], v24 offset:896
	ds_read_b128 v[228:231], v24 offset:192
	ds_read_b128 v[232:235], v24 offset:448
	ds_read_b128 v[236:239], v24 offset:704
	ds_read_b128 v[240:243], v24 offset:960
	v_add_f32_e32 v148, v148, v190
	v_fmamk_f32 v148, v148, 0x3c800000, v165
	v_rsq_f32_e32 v148, v148
	v_add_f32_e32 v158, 1.0, v158
	v_rcp_f32_e32 v158, v158
	s_mov_b32 s58, 0x7160000
	v_mul_f32_e32 v148, v16, v148
	s_waitcnt vmcnt(0)
	v_mul_f32_e32 v148, v149, v148
	v_mul_f32_e32 v158, v93, v158
	v_mul_f32_e32 v148, v158, v148
	v_lshl_add_u64 v[158:159], s[48:49], 0, v[26:27]
	v_add_co_u32_e32 v162, vcc, s58, v158
	v_cvt_pk_bf16_f32 v148, v148, s0
	s_nop 0
	v_addc_co_u32_e32 v163, vcc, 0, v159, vcc
	v_mul_f32_e32 v161, 0xbfb8aa3b, v92
	global_store_short v[162:163], v148, off offset:3072
	v_add_f32_e32 v148, v179, v183
	v_exp_f32_e32 v161, v161
	v_add_f32_e32 v148, v148, v187
	v_add_f32_e32 v148, v148, v191
	v_fmamk_f32 v148, v148, 0x3c800000, v165
	v_rsq_f32_e32 v148, v148
	v_add_f32_e32 v161, 1.0, v161
	v_rcp_f32_e32 v161, v161
	s_mov_b32 s58, 0x7161000
	v_mul_f32_e32 v148, v17, v148
	v_mul_f32_e32 v148, v149, v148
	v_mul_f32_e32 v161, v92, v161
	v_mul_f32_e32 v148, v161, v148
	v_add_co_u32_e32 v162, vcc, s58, v158
	v_cvt_pk_bf16_f32 v148, v148, s0
	s_nop 0
	v_addc_co_u32_e32 v163, vcc, 0, v159, vcc
	v_mul_f32_e32 v161, 0xbfb8aa3b, v95
	global_store_short v[162:163], v148, off offset:1024
	v_add_f32_e32 v148, v180, v184
	v_exp_f32_e32 v161, v161
	v_add_f32_e32 v148, v148, v188
	v_add_f32_e32 v148, v148, v192
	v_fmamk_f32 v148, v148, 0x3c800000, v165
	v_rsq_f32_e32 v148, v148
	v_add_f32_e32 v161, 1.0, v161
	v_rcp_f32_e32 v161, v161
	v_mul_f32_e32 v148, v18, v148
	v_mul_f32_e32 v148, v149, v148
	v_mul_f32_e32 v161, v95, v161
	v_mul_f32_e32 v148, v161, v148
	v_cvt_pk_bf16_f32 v148, v148, s0
	v_mul_f32_e32 v161, 0xbfb8aa3b, v94
	global_store_short v[162:163], v148, off offset:3072
	v_add_f32_e32 v148, v181, v185
	v_exp_f32_e32 v161, v161
	v_add_f32_e32 v148, v148, v189
	v_add_f32_e32 v148, v148, v193
	v_fmamk_f32 v148, v148, 0x3c800000, v165
	v_rsq_f32_e32 v148, v148
	v_add_f32_e32 v161, 1.0, v161
	v_rcp_f32_e32 v161, v161
	v_add_co_u32_e32 v162, vcc, 0x7162000, v158
	v_mul_f32_e32 v148, v19, v148
	v_mul_f32_e32 v148, v149, v148
	v_mul_f32_e32 v161, v94, v161
	v_mul_f32_e32 v148, v161, v148
	v_cvt_pk_bf16_f32 v148, v148, s0
	v_addc_co_u32_e32 v163, vcc, 0, v159, vcc
	global_store_short v[162:163], v148, off offset:1024
	s_waitcnt lgkmcnt(0)
	s_and_saveexec_b64 s[58:59], s[22:23]
	s_cbranch_execz .LBB0_175
	v_mov_b32_e32 v162, v196
	v_mov_b32_e32 v163, v200
	s_waitcnt lgkmcnt(0)
	v_add_f32_e32 v148, v162, v163
	v_mov_b32_e32 v162, v204
	v_mov_b32_e32 v163, v208
	s_waitcnt lgkmcnt(0)
	v_add_f32_e32 v148, v148, v162
	v_add_f32_e32 v148, v148, v163
	v_fmamk_f32 v148, v148, 0x3c800000, v165
	v_rsq_f32_e32 v148, v148
	s_nop 0
	v_mul_f32_e32 v163, v20, v148
	v_mul_f32_e32 v148, 0xbfb8aa3b, v96
	v_exp_f32_e32 v148, v148
	s_nop 0
	v_add_f32_e32 v148, 1.0, v148
	v_rcp_f32_e32 v162, v148
	v_mov_b32_e32 v148, v96
	v_pk_mul_f32 v[162:163], v[148:149], v[162:163]
	s_nop 0
	v_mul_f32_e32 v148, v162, v163
	v_add_co_u32_e32 v162, vcc, 0x7168000, v158
	v_cvt_pk_bf16_f32 v148, v148, s0
	s_nop 0
	v_addc_co_u32_e32 v163, vcc, 0, v159, vcc
	global_store_short v[162:163], v148, off offset:3072
	s_or_b64 exec, exec, s[58:59]
	s_and_saveexec_b64 s[58:59], s[24:25]
	s_cbranch_execnz .LBB0_176

; #define LAS __attribute__((address_space(3)))
; __device__ __forceinline__ unsigned f2bf(float f) { const f32x2_ v = {f, 0.f}; const bf16x2_ b = __builtin_convertvector(v, bf16x2_); return __builtin_bit_cast(unsigned, b) & 0xffffu; }
; __device__ __forceinline__ float siluf_(float x) { return x * sigmoidf_(x); }
; __device__ __forceinline__ void g2_phase(const PP P, int l, LAS unsigned char* lds) {
;     ...
;             if (act) {
; #pragma unroll
;                 for (int mi = 0; mi < 4; ++mi)
; #pragma unroll
;                     for (int j = 0; j < 4; ++j) { const int i = 16 * mi + fq * 4 + j; LAS float* rp = red + (n & 1) * 256 + i;
;                         const float tot = rp[0] + rp[64] + rp[128] + rp[192]; const float rinv = __builtin_amdgcn_rsqf(tot * (1.0f / 64.0f) + 1e-6f);
;                         if (i < L) { const size_t row = seq0 + (size_t)n * 64 + i;
;                             MIX[row * 1024 + 512 + h * 64 + dv] = (bf16)f2bf(O[mi][j] * rinv * gnw * siluf_(zr[mi][j])); } }
;             }
.LBB0_166:
	v_mov_b32_e32 v162, v198
	v_mov_b32_e32 v163, v202
	s_waitcnt lgkmcnt(0)
	v_add_f32_e32 v148, v162, v163
	v_mov_b32_e32 v162, v206
	v_mov_b32_e32 v163, v210
	s_waitcnt lgkmcnt(0)
	v_add_f32_e32 v148, v148, v162
	v_add_f32_e32 v148, v148, v163
	v_fmamk_f32 v148, v148, 0x3c800000, v165
	v_rsq_f32_e32 v148, v148
	s_nop 0
	v_mul_f32_e32 v163, v22, v148
	v_mul_f32_e32 v148, 0xbfb8aa3b, v98
	v_exp_f32_e32 v148, v148
	s_nop 0
	v_add_f32_e32 v148, 1.0, v148
	v_rcp_f32_e32 v162, v148
	v_mov_b32_e32 v148, v98
	v_pk_mul_f32 v[162:163], v[148:149], v[162:163]
	s_nop 0
	v_mul_f32_e32 v148, v162, v163
	v_add_co_u32_e32 v162, vcc, 0x7169000, v158
	v_cvt_pk_bf16_f32 v148, v148, s0
	s_nop 0
	v_addc_co_u32_e32 v163, vcc, 0, v159, vcc
	global_store_short v[162:163], v148, off offset:3072
	s_or_b64 exec, exec, s[58:59]
	s_and_saveexec_b64 s[58:59], s[28:29]
	s_cbranch_execnz .LBB0_178

; #define LAS __attribute__((address_space(3)))
; __device__ __forceinline__ unsigned f2bf(float f) { const f32x2_ v = {f, 0.f}; const bf16x2_ b = __builtin_convertvector(v, bf16x2_); return __builtin_bit_cast(unsigned, b) & 0xffffu; }
; __device__ __forceinline__ float siluf_(float x) { return x * sigmoidf_(x); }
; __device__ __forceinline__ void g2_phase(const PP P, int l, LAS unsigned char* lds) {
;     ...
;             if (act) {
; #pragma unroll
;                 for (int mi = 0; mi < 4; ++mi)
; #pragma unroll
;                     for (int j = 0; j < 4; ++j) { const int i = 16 * mi + fq * 4 + j; LAS float* rp = red + (n & 1) * 256 + i;
;                         const float tot = rp[0] + rp[64] + rp[128] + rp[192]; const float rinv = __builtin_amdgcn_rsqf(tot * (1.0f / 64.0f) + 1e-6f);
;                         if (i < L) { const size_t row = seq0 + (size_t)n * 64 + i;
;                             MIX[row * 1024 + 512 + h * 64 + dv] = (bf16)f2bf(O[mi][j] * rinv * gnw * siluf_(zr[mi][j])); } }
;             }
.LBB0_168:
	v_mov_b32_e32 v162, v212
	v_mov_b32_e32 v163, v216
	s_waitcnt lgkmcnt(0)
	v_add_f32_e32 v148, v162, v163
	v_mov_b32_e32 v162, v220
	v_mov_b32_e32 v163, v224
	s_waitcnt lgkmcnt(0)
	v_add_f32_e32 v148, v148, v162
	v_add_f32_e32 v148, v148, v163
	v_fmamk_f32 v148, v148, 0x3c800000, v165
	v_rsq_f32_e32 v148, v148
	s_nop 0
	v_mul_f32_e32 v163, v28, v148
	v_mul_f32_e32 v148, 0xbfb8aa3b, v100
	v_exp_f32_e32 v148, v148
	s_nop 0
	v_add_f32_e32 v148, 1.0, v148
	v_rcp_f32_e32 v162, v148
	v_mov_b32_e32 v148, v100
	v_pk_mul_f32 v[162:163], v[148:149], v[162:163]
	s_nop 0
	v_mul_f32_e32 v148, v162, v163
	v_add_co_u32_e32 v162, vcc, 0x7170000, v158
	v_cvt_pk_bf16_f32 v148, v148, s0
	s_nop 0
	v_addc_co_u32_e32 v163, vcc, 0, v159, vcc
	global_store_short v[162:163], v148, off offset:3072
	s_or_b64 exec, exec, s[58:59]
	s_and_saveexec_b64 s[58:59], s[34:35]
	s_cbranch_execnz .LBB0_180

; #define LAS __attribute__((address_space(3)))
; __device__ __forceinline__ unsigned f2bf(float f) { const f32x2_ v = {f, 0.f}; const bf16x2_ b = __builtin_convertvector(v, bf16x2_); return __builtin_bit_cast(unsigned, b) & 0xffffu; }
; __device__ __forceinline__ float siluf_(float x) { return x * sigmoidf_(x); }
; __device__ __forceinline__ void g2_phase(const PP P, int l, LAS unsigned char* lds) {
;     ...
;             if (act) {
; #pragma unroll
;                 for (int mi = 0; mi < 4; ++mi)
; #pragma unroll
;                     for (int j = 0; j < 4; ++j) { const int i = 16 * mi + fq * 4 + j; LAS float* rp = red + (n & 1) * 256 + i;
;                         const float tot = rp[0] + rp[64] + rp[128] + rp[192]; const float rinv = __builtin_amdgcn_rsqf(tot * (1.0f / 64.0f) + 1e-6f);
;                         if (i < L) { const size_t row = seq0 + (size_t)n * 64 + i;
;                             MIX[row * 1024 + 512 + h * 64 + dv] = (bf16)f2bf(O[mi][j] * rinv * gnw * siluf_(zr[mi][j])); } }
;             }
.LBB0_170:
	v_mov_b32_e32 v162, v214
	v_mov_b32_e32 v163, v218
	s_waitcnt lgkmcnt(0)
	v_add_f32_e32 v148, v162, v163
	v_mov_b32_e32 v162, v222
	v_mov_b32_e32 v163, v226
	s_waitcnt lgkmcnt(0)
	v_add_f32_e32 v148, v148, v162
	v_add_f32_e32 v148, v148, v163
	v_fmamk_f32 v148, v148, 0x3c800000, v165
	v_rsq_f32_e32 v148, v148
	s_nop 0
	v_mul_f32_e32 v163, v30, v148
	v_mul_f32_e32 v148, 0xbfb8aa3b, v102
	v_exp_f32_e32 v148, v148
	s_nop 0
	v_add_f32_e32 v148, 1.0, v148
	v_rcp_f32_e32 v162, v148
	v_mov_b32_e32 v148, v102
	v_pk_mul_f32 v[162:163], v[148:149], v[162:163]
	s_nop 0
	v_mul_f32_e32 v148, v162, v163
	v_add_co_u32_e32 v162, vcc, 0x7171000, v158
	v_cvt_pk_bf16_f32 v148, v148, s0
	s_nop 0
	v_addc_co_u32_e32 v163, vcc, 0, v159, vcc
	global_store_short v[162:163], v148, off offset:3072
	s_or_b64 exec, exec, s[58:59]
	s_and_saveexec_b64 s[58:59], s[38:39]
	s_cbranch_execnz .LBB0_182

; #define LAS __attribute__((address_space(3)))
; __device__ __forceinline__ unsigned f2bf(float f) { const f32x2_ v = {f, 0.f}; const bf16x2_ b = __builtin_convertvector(v, bf16x2_); return __builtin_bit_cast(unsigned, b) & 0xffffu; }
; __device__ __forceinline__ float siluf_(float x) { return x * sigmoidf_(x); }
; __device__ __forceinline__ void g2_phase(const PP P, int l, LAS unsigned char* lds) {
;     ...
;             if (act) {
; #pragma unroll
;                 for (int mi = 0; mi < 4; ++mi)
; #pragma unroll
;                     for (int j = 0; j < 4; ++j) { const int i = 16 * mi + fq * 4 + j; LAS float* rp = red + (n & 1) * 256 + i;
;                         const float tot = rp[0] + rp[64] + rp[128] + rp[192]; const float rinv = __builtin_amdgcn_rsqf(tot * (1.0f / 64.0f) + 1e-6f);
;                         if (i < L) { const size_t row = seq0 + (size_t)n * 64 + i;
;                             MIX[row * 1024 + 512 + h * 64 + dv] = (bf16)f2bf(O[mi][j] * rinv * gnw * siluf_(zr[mi][j])); } }
;             }
.LBB0_172:
	v_mov_b32_e32 v162, v228
	v_mov_b32_e32 v163, v232
	s_waitcnt lgkmcnt(0)
	v_add_f32_e32 v148, v162, v163
	v_mov_b32_e32 v162, v236
	v_mov_b32_e32 v163, v240
	s_waitcnt lgkmcnt(0)
	v_add_f32_e32 v148, v148, v162
	v_add_f32_e32 v148, v148, v163
	v_fmamk_f32 v148, v148, 0x3c800000, v165
	v_rsq_f32_e32 v148, v148
	s_nop 0
	v_mul_f32_e32 v163, v36, v148
	v_mul_f32_e32 v148, 0xbfb8aa3b, v154
	v_exp_f32_e32 v148, v148
	s_nop 0
	v_add_f32_e32 v148, 1.0, v148
	v_rcp_f32_e32 v162, v148
	v_mov_b32_e32 v148, v154
	v_pk_mul_f32 v[162:163], v[148:149], v[162:163]
	s_nop 0
	v_mul_f32_e32 v148, v162, v163
	v_add_co_u32_e32 v162, vcc, 0x7178000, v158
	v_cvt_pk_bf16_f32 v148, v148, s0
	s_nop 0
	v_addc_co_u32_e32 v163, vcc, 0, v159, vcc
	global_store_short v[162:163], v148, off offset:3072
	s_or_b64 exec, exec, s[58:59]
	s_and_saveexec_b64 s[58:59], s[42:43]
	s_cbranch_execnz .LBB0_184

; #define LAS __attribute__((address_space(3)))
; __device__ __forceinline__ unsigned f2bf(float f) { const f32x2_ v = {f, 0.f}; const bf16x2_ b = __builtin_convertvector(v, bf16x2_); return __builtin_bit_cast(unsigned, b) & 0xffffu; }
; __device__ __forceinline__ float siluf_(float x) { return x * sigmoidf_(x); }
; __device__ __forceinline__ void g2_phase(const PP P, int l, LAS unsigned char* lds) {
;     ...
;             if (act) {
; #pragma unroll
;                 for (int mi = 0; mi < 4; ++mi)
; #pragma unroll
;                     for (int j = 0; j < 4; ++j) { const int i = 16 * mi + fq * 4 + j; LAS float* rp = red + (n & 1) * 256 + i;
;                         const float tot = rp[0] + rp[64] + rp[128] + rp[192]; const float rinv = __builtin_amdgcn_rsqf(tot * (1.0f / 64.0f) + 1e-6f);
;                         if (i < L) { const size_t row = seq0 + (size_t)n * 64 + i;
;                             MIX[row * 1024 + 512 + h * 64 + dv] = (bf16)f2bf(O[mi][j] * rinv * gnw * siluf_(zr[mi][j])); } }
;             }
.LBB0_174:
	v_mov_b32_e32 v162, v230
	v_mov_b32_e32 v163, v234
	s_waitcnt lgkmcnt(0)
	v_add_f32_e32 v148, v162, v163
	v_mov_b32_e32 v162, v238
	v_mov_b32_e32 v163, v242
	s_waitcnt lgkmcnt(0)
	v_add_f32_e32 v148, v148, v162
	v_add_f32_e32 v148, v148, v163
	v_fmamk_f32 v148, v148, 0x3c800000, v165
	v_rsq_f32_e32 v148, v148
	s_nop 0
	v_mul_f32_e32 v163, v38, v148
	v_mul_f32_e32 v148, 0xbfb8aa3b, v156
	v_exp_f32_e32 v148, v148
	s_nop 0
	v_add_f32_e32 v148, 1.0, v148
	v_rcp_f32_e32 v162, v148
	v_mov_b32_e32 v148, v156
	v_pk_mul_f32 v[162:163], v[148:149], v[162:163]
	s_nop 0
	v_mul_f32_e32 v148, v162, v163
	v_add_co_u32_e32 v162, vcc, 0x7179000, v158
	v_cvt_pk_bf16_f32 v148, v148, s0
	s_nop 0
	v_addc_co_u32_e32 v163, vcc, 0, v159, vcc
	global_store_short v[162:163], v148, off offset:3072
	s_or_b64 exec, exec, s[58:59]
	s_and_b64 exec, exec, s[46:47]
	s_cbranch_execz .LBB0_120
	s_branch .LBB0_186

; #define LAS __attribute__((address_space(3)))
; __device__ __forceinline__ unsigned f2bf(float f) { const f32x2_ v = {f, 0.f}; const bf16x2_ b = __builtin_convertvector(v, bf16x2_); return __builtin_bit_cast(unsigned, b) & 0xffffu; }
; __device__ __forceinline__ float siluf_(float x) { return x * sigmoidf_(x); }
; __device__ __forceinline__ void g2_phase(const PP P, int l, LAS unsigned char* lds) {
;     ...
;             if (act) {
; #pragma unroll
;                 for (int mi = 0; mi < 4; ++mi)
; #pragma unroll
;                     for (int j = 0; j < 4; ++j) { const int i = 16 * mi + fq * 4 + j; LAS float* rp = red + (n & 1) * 256 + i;
;                         const float tot = rp[0] + rp[64] + rp[128] + rp[192]; const float rinv = __builtin_amdgcn_rsqf(tot * (1.0f / 64.0f) + 1e-6f);
;                         if (i < L) { const size_t row = seq0 + (size_t)n * 64 + i;
;                             MIX[row * 1024 + 512 + h * 64 + dv] = (bf16)f2bf(O[mi][j] * rinv * gnw * siluf_(zr[mi][j])); } }
;             }
.LBB0_176:
	v_mov_b32_e32 v162, v197
	v_mov_b32_e32 v163, v201
	s_waitcnt lgkmcnt(0)
	v_add_f32_e32 v148, v162, v163
	v_mov_b32_e32 v162, v205
	v_mov_b32_e32 v163, v209
	s_waitcnt lgkmcnt(0)
	v_add_f32_e32 v148, v148, v162
	v_add_f32_e32 v148, v148, v163
	v_fmamk_f32 v148, v148, 0x3c800000, v165
	v_rsq_f32_e32 v148, v148
	s_nop 0
	v_mul_f32_e32 v163, v21, v148
	v_mul_f32_e32 v148, 0xbfb8aa3b, v97
	v_exp_f32_e32 v148, v148
	s_nop 0
	v_add_f32_e32 v148, 1.0, v148
	v_rcp_f32_e32 v162, v148
	v_mov_b32_e32 v148, v97
	v_pk_mul_f32 v[162:163], v[148:149], v[162:163]
	s_nop 0
	v_mul_f32_e32 v148, v162, v163
	v_add_co_u32_e32 v162, vcc, 0x7169000, v158
	v_cvt_pk_bf16_f32 v148, v148, s0
	s_nop 0
	v_addc_co_u32_e32 v163, vcc, 0, v159, vcc
	global_store_short v[162:163], v148, off offset:1024
	s_or_b64 exec, exec, s[58:59]
	s_and_saveexec_b64 s[58:59], s[26:27]
	s_cbranch_execnz .LBB0_166

; #define LAS __attribute__((address_space(3)))
; __device__ __forceinline__ unsigned f2bf(float f) { const f32x2_ v = {f, 0.f}; const bf16x2_ b = __builtin_convertvector(v, bf16x2_); return __builtin_bit_cast(unsigned, b) & 0xffffu; }
; __device__ __forceinline__ float siluf_(float x) { return x * sigmoidf_(x); }
; __device__ __forceinline__ void g2_phase(const PP P, int l, LAS unsigned char* lds) {
;     ...
;             if (act) {
; #pragma unroll
;                 for (int mi = 0; mi < 4; ++mi)
; #pragma unroll
;                     for (int j = 0; j < 4; ++j) { const int i = 16 * mi + fq * 4 + j; LAS float* rp = red + (n & 1) * 256 + i;
;                         const float tot = rp[0] + rp[64] + rp[128] + rp[192]; const float rinv = __builtin_amdgcn_rsqf(tot * (1.0f / 64.0f) + 1e-6f);
;                         if (i < L) { const size_t row = seq0 + (size_t)n * 64 + i;
;                             MIX[row * 1024 + 512 + h * 64 + dv] = (bf16)f2bf(O[mi][j] * rinv * gnw * siluf_(zr[mi][j])); } }
;             }
.LBB0_178:
	v_mov_b32_e32 v162, v199
	v_mov_b32_e32 v163, v203
	s_waitcnt lgkmcnt(0)
	v_add_f32_e32 v148, v162, v163
	v_mov_b32_e32 v162, v207
	v_mov_b32_e32 v163, v211
	s_waitcnt lgkmcnt(0)
	v_add_f32_e32 v148, v148, v162
	v_add_f32_e32 v148, v148, v163
	v_fmamk_f32 v148, v148, 0x3c800000, v165
	v_rsq_f32_e32 v148, v148
	s_nop 0
	v_mul_f32_e32 v163, v23, v148
	v_mul_f32_e32 v148, 0xbfb8aa3b, v99
	v_exp_f32_e32 v148, v148
	s_nop 0
	v_add_f32_e32 v148, 1.0, v148
	v_rcp_f32_e32 v162, v148
	v_mov_b32_e32 v148, v99
	v_pk_mul_f32 v[162:163], v[148:149], v[162:163]
	s_nop 0
	v_mul_f32_e32 v148, v162, v163
	v_add_co_u32_e32 v162, vcc, 0x716a000, v158
	v_cvt_pk_bf16_f32 v148, v148, s0
	s_nop 0
	v_addc_co_u32_e32 v163, vcc, 0, v159, vcc
	global_store_short v[162:163], v148, off offset:1024
	s_or_b64 exec, exec, s[58:59]
	s_and_saveexec_b64 s[58:59], s[30:31]
	s_cbranch_execnz .LBB0_168

; #define LAS __attribute__((address_space(3)))
; __device__ __forceinline__ unsigned f2bf(float f) { const f32x2_ v = {f, 0.f}; const bf16x2_ b = __builtin_convertvector(v, bf16x2_); return __builtin_bit_cast(unsigned, b) & 0xffffu; }
; __device__ __forceinline__ float siluf_(float x) { return x * sigmoidf_(x); }
; __device__ __forceinline__ void g2_phase(const PP P, int l, LAS unsigned char* lds) {
;     ...
;             if (act) {
; #pragma unroll
;                 for (int mi = 0; mi < 4; ++mi)
; #pragma unroll
;                     for (int j = 0; j < 4; ++j) { const int i = 16 * mi + fq * 4 + j; LAS float* rp = red + (n & 1) * 256 + i;
;                         const float tot = rp[0] + rp[64] + rp[128] + rp[192]; const float rinv = __builtin_amdgcn_rsqf(tot * (1.0f / 64.0f) + 1e-6f);
;                         if (i < L) { const size_t row = seq0 + (size_t)n * 64 + i;
;                             MIX[row * 1024 + 512 + h * 64 + dv] = (bf16)f2bf(O[mi][j] * rinv * gnw * siluf_(zr[mi][j])); } }
;             }
.LBB0_180:
	v_mov_b32_e32 v162, v213
	v_mov_b32_e32 v163, v217
	s_waitcnt lgkmcnt(0)
	v_add_f32_e32 v148, v162, v163
	v_mov_b32_e32 v162, v221
	v_mov_b32_e32 v163, v225
	s_waitcnt lgkmcnt(0)
	v_add_f32_e32 v148, v148, v162
	v_add_f32_e32 v148, v148, v163
	v_fmamk_f32 v148, v148, 0x3c800000, v165
	v_rsq_f32_e32 v148, v148
	s_nop 0
	v_mul_f32_e32 v163, v29, v148
	v_mul_f32_e32 v148, 0xbfb8aa3b, v101
	v_exp_f32_e32 v148, v148
	s_nop 0
	v_add_f32_e32 v148, 1.0, v148
	v_rcp_f32_e32 v162, v148
	v_mov_b32_e32 v148, v101
	v_pk_mul_f32 v[162:163], v[148:149], v[162:163]
	s_nop 0
	v_mul_f32_e32 v148, v162, v163
	v_add_co_u32_e32 v162, vcc, 0x7171000, v158
	v_cvt_pk_bf16_f32 v148, v148, s0
	s_nop 0
	v_addc_co_u32_e32 v163, vcc, 0, v159, vcc
	global_store_short v[162:163], v148, off offset:1024
	s_or_b64 exec, exec, s[58:59]
	s_and_saveexec_b64 s[58:59], s[36:37]
	s_cbranch_execnz .LBB0_170

; #define LAS __attribute__((address_space(3)))
; __device__ __forceinline__ unsigned f2bf(float f) { const f32x2_ v = {f, 0.f}; const bf16x2_ b = __builtin_convertvector(v, bf16x2_); return __builtin_bit_cast(unsigned, b) & 0xffffu; }
; __device__ __forceinline__ float siluf_(float x) { return x * sigmoidf_(x); }
; __device__ __forceinline__ void g2_phase(const PP P, int l, LAS unsigned char* lds) {
;     ...
;             if (act) {
; #pragma unroll
;                 for (int mi = 0; mi < 4; ++mi)
; #pragma unroll
;                     for (int j = 0; j < 4; ++j) { const int i = 16 * mi + fq * 4 + j; LAS float* rp = red + (n & 1) * 256 + i;
;                         const float tot = rp[0] + rp[64] + rp[128] + rp[192]; const float rinv = __builtin_amdgcn_rsqf(tot * (1.0f / 64.0f) + 1e-6f);
;                         if (i < L) { const size_t row = seq0 + (size_t)n * 64 + i;
;                             MIX[row * 1024 + 512 + h * 64 + dv] = (bf16)f2bf(O[mi][j] * rinv * gnw * siluf_(zr[mi][j])); } }
;             }
.LBB0_182:
	v_mov_b32_e32 v162, v215
	v_mov_b32_e32 v163, v219
	s_waitcnt lgkmcnt(0)
	v_add_f32_e32 v148, v162, v163
	v_mov_b32_e32 v162, v223
	v_mov_b32_e32 v163, v227
	s_waitcnt lgkmcnt(0)
	v_add_f32_e32 v148, v148, v162
	v_add_f32_e32 v148, v148, v163
	v_fmamk_f32 v148, v148, 0x3c800000, v165
	v_rsq_f32_e32 v148, v148
	s_nop 0
	v_mul_f32_e32 v163, v31, v148
	v_mul_f32_e32 v148, 0xbfb8aa3b, v103
	v_exp_f32_e32 v148, v148
	s_nop 0
	v_add_f32_e32 v148, 1.0, v148
	v_rcp_f32_e32 v162, v148
	v_mov_b32_e32 v148, v103
	v_pk_mul_f32 v[162:163], v[148:149], v[162:163]
	s_nop 0
	v_mul_f32_e32 v148, v162, v163
	v_add_co_u32_e32 v162, vcc, 0x7172000, v158
	v_cvt_pk_bf16_f32 v148, v148, s0
	s_nop 0
	v_addc_co_u32_e32 v163, vcc, 0, v159, vcc
	global_store_short v[162:163], v148, off offset:1024
	s_or_b64 exec, exec, s[58:59]
	s_and_saveexec_b64 s[58:59], s[40:41]
	s_cbranch_execnz .LBB0_172

; #define LAS __attribute__((address_space(3)))
; __device__ __forceinline__ unsigned f2bf(float f) { const f32x2_ v = {f, 0.f}; const bf16x2_ b = __builtin_convertvector(v, bf16x2_); return __builtin_bit_cast(unsigned, b) & 0xffffu; }
; __device__ __forceinline__ float siluf_(float x) { return x * sigmoidf_(x); }
; __device__ __forceinline__ void g2_phase(const PP P, int l, LAS unsigned char* lds) {
;     ...
;             if (act) {
; #pragma unroll
;                 for (int mi = 0; mi < 4; ++mi)
; #pragma unroll
;                     for (int j = 0; j < 4; ++j) { const int i = 16 * mi + fq * 4 + j; LAS float* rp = red + (n & 1) * 256 + i;
;                         const float tot = rp[0] + rp[64] + rp[128] + rp[192]; const float rinv = __builtin_amdgcn_rsqf(tot * (1.0f / 64.0f) + 1e-6f);
;                         if (i < L) { const size_t row = seq0 + (size_t)n * 64 + i;
;                             MIX[row * 1024 + 512 + h * 64 + dv] = (bf16)f2bf(O[mi][j] * rinv * gnw * siluf_(zr[mi][j])); } }
;             }
.LBB0_184:
	v_mov_b32_e32 v162, v229
	v_mov_b32_e32 v163, v233
	s_waitcnt lgkmcnt(0)
	v_add_f32_e32 v148, v162, v163
	v_mov_b32_e32 v162, v237
	v_mov_b32_e32 v163, v241
	s_waitcnt lgkmcnt(0)
	v_add_f32_e32 v148, v148, v162
	v_add_f32_e32 v148, v148, v163
	v_fmamk_f32 v148, v148, 0x3c800000, v165
	v_rsq_f32_e32 v148, v148
	s_nop 0
	v_mul_f32_e32 v163, v37, v148
	v_mul_f32_e32 v148, 0xbfb8aa3b, v155
	v_exp_f32_e32 v148, v148
	s_nop 0
	v_add_f32_e32 v148, 1.0, v148
	v_rcp_f32_e32 v162, v148
	v_mov_b32_e32 v148, v155
	v_pk_mul_f32 v[162:163], v[148:149], v[162:163]
	s_nop 0
	v_mul_f32_e32 v148, v162, v163
	v_add_co_u32_e32 v162, vcc, 0x7179000, v158
	v_cvt_pk_bf16_f32 v148, v148, s0
	s_nop 0
	v_addc_co_u32_e32 v163, vcc, 0, v159, vcc
	global_store_short v[162:163], v148, off offset:1024
	s_or_b64 exec, exec, s[58:59]
	s_and_saveexec_b64 s[58:59], s[44:45]
	s_cbranch_execnz .LBB0_174

; #define LAS __attribute__((address_space(3)))
; __device__ __forceinline__ unsigned f2bf(float f) { const f32x2_ v = {f, 0.f}; const bf16x2_ b = __builtin_convertvector(v, bf16x2_); return __builtin_bit_cast(unsigned, b) & 0xffffu; }
; __device__ __forceinline__ float siluf_(float x) { return x * sigmoidf_(x); }
; __device__ __forceinline__ void g2_phase(const PP P, int l, LAS unsigned char* lds) {
;     ...
;             if (act) {
; #pragma unroll
;                 for (int mi = 0; mi < 4; ++mi)
; #pragma unroll
;                     for (int j = 0; j < 4; ++j) { const int i = 16 * mi + fq * 4 + j; LAS float* rp = red + (n & 1) * 256 + i;
;                         const float tot = rp[0] + rp[64] + rp[128] + rp[192]; const float rinv = __builtin_amdgcn_rsqf(tot * (1.0f / 64.0f) + 1e-6f);
;                         if (i < L) { const size_t row = seq0 + (size_t)n * 64 + i;
;                             MIX[row * 1024 + 512 + h * 64 + dv] = (bf16)f2bf(O[mi][j] * rinv * gnw * siluf_(zr[mi][j])); } }
;             }
.LBB0_186:
	v_mov_b32_e32 v162, v231
	v_mov_b32_e32 v163, v235
	v_add_co_u32_e32 v158, vcc, 0x717a000, v158
	s_waitcnt lgkmcnt(0)
	v_add_f32_e32 v148, v162, v163
	v_mov_b32_e32 v162, v239
	v_mov_b32_e32 v163, v243
	v_addc_co_u32_e32 v159, vcc, 0, v159, vcc
	s_waitcnt lgkmcnt(0)
	v_add_f32_e32 v24, v148, v162
	v_add_f32_e32 v24, v24, v163
	v_fmamk_f32 v24, v24, 0x3c800000, v165
	v_rsq_f32_e32 v24, v24
	v_mov_b32_e32 v148, v157
	v_mul_f32_e32 v163, v39, v24
	v_mul_f32_e32 v24, 0xbfb8aa3b, v157
	v_exp_f32_e32 v24, v24
	s_nop 0
	v_add_f32_e32 v24, 1.0, v24
	v_rcp_f32_e32 v162, v24
	s_nop 0
	v_pk_mul_f32 v[162:163], v[148:149], v[162:163]
	s_nop 0
	v_mul_f32_e32 v24, v162, v163
	v_cvt_pk_bf16_f32 v24, v24, s0
	global_store_short v[158:159], v24, off offset:1024
	s_branch .LBB0_120
